# G3->G4, G4->G5, G5->G6 barriers release only the local XCD when a run-time check finds every blockIdx&7 group on one hardware XCC (else the full grid barrier as before)
# speedup vs baseline: 1.0114x; 1.0025x over previous
; #define LAS __attribute__((address_space(3)))
; __global__ void __launch_bounds__(512, 2) fwd_mega(Args a) {
;     ...
;     const int G = gridDim.x, bx = blockIdx.x, ngw = G * 8;
;     unsigned char* ws = a.ws;
;     float* ada = (float*)(ws + WS_ADA); unsigned* ctl = (unsigned*)(ws + WS_CTL); float* rowss = (float*)(ws + WS_ROWSS); float* bias2 = (float*)(ws + WS_BIAS2);
;     bf16* WinT = (bf16*)(ws + WS_WIN); bf16* WattT = (bf16*)(ws + WS_WATT); bf16* WmlT = (bf16*)(ws + WS_WML); bf16* WoutT = (bf16*)(ws + WS_WOUT); bf16* Wff1T = (bf16*)(ws + WS_WFF1); bf16* Wff2T = (bf16*)(ws + WS_WFF2);
;     float* IFg = (float*)(ws + WS_IF); bf16* U = (bf16*)(ws + WS_U); bf16* P = (bf16*)(ws + WS_P); bf16* HID = (bf16*)(ws + WS_HID); bf16* OG = (bf16*)(ws + WS_OG); bf16* YPRE = (bf16*)(ws + WS_YPRE);
;     float* LSE = (float*)(ws + WS_LSE); bf16* Hb = (bf16*)(ws + WS_H); bf16* ATT = (bf16*)(ws + WS_ATT);
;     const float* x = a.in[0]; float* out = a.out;
;     volatile LAS unsigned* bst = (volatile LAS unsigned*)(lds + LDS_BYTES - 16);
;     if (threadIdx.x == 0) { bst[0] = 0u; bst[1] = 0u; }
;     __syncthreads();
;     (void)xcd_barrier_post(ctl + 4096, bst);
.LBB0_142:
	s_or_b64 exec, exec, s[0:1]
	v_readlane_b32 s12, v251, 8
	v_readlane_b32 s13, v251, 9
	s_add_u32 s0, s12, 0xc0000
	v_readlane_b32 s14, v251, 10
	v_readlane_b32 s15, v251, 11
	v_writelane_b32 v251, s0, 46
	s_addc_u32 s0, s13, 0
	v_writelane_b32 v251, s0, 47
	s_add_u32 s0, s12, 0x100000
	v_writelane_b32 v251, s0, 48
	s_addc_u32 s0, s13, 0
	v_writelane_b32 v251, s0, 49
	s_add_u32 s0, s12, 0x2c00000
	v_writelane_b32 v251, s0, 50
	s_addc_u32 s0, s13, 0
	v_writelane_b32 v251, s0, 51
	s_add_u32 s0, s12, 0x3000000
	v_writelane_b32 v251, s0, 52
	s_addc_u32 s0, s13, 0
	s_add_u32 s86, s12, 0xb000000
	s_addc_u32 s87, s13, 0
	s_add_u32 s88, s12, 0x31000000
	s_addc_u32 s89, s13, 0
	s_add_u32 s90, s12, 0x37000000
	s_addc_u32 s91, s13, 0
	s_add_u32 s16, s12, 0x37200000
	s_addc_u32 s17, s13, 0
	s_add_u32 s92, s12, 0x3b200000
	s_addc_u32 s93, s13, 0
	s_cmpk_lt_i32 s51, 0x1300
	v_writelane_b32 v251, s0, 53
	s_cselect_b64 s[0:1], -1, 0
	v_writelane_b32 v251, s0, 54
	s_ashr_i32 s94, s51, 31
	s_ashr_i32 s95, s14, 31
	v_writelane_b32 v251, s1, 55
	s_lshr_b32 s0, s94, 29
	s_add_i32 s0, s51, s0
	s_ashr_i32 s1, s0, 3
	s_and_b32 s0, s0, -8
	s_sub_i32 s0, s51, s0
	s_add_u32 s2, s12, 0x1500000
	s_addc_u32 s3, s13, 0
	v_writelane_b32 v251, s2, 56
	s_cmpk_lt_i32 s51, 0x80
	v_mov_b32_e32 v1, 0
	v_writelane_b32 v251, s3, 57
	s_cselect_b64 s[2:3], -1, 0
	v_writelane_b32 v251, s2, 58
	v_mov_b32_e32 v250, 0x2000
	v_mov_b32_e32 v189, 1
	v_writelane_b32 v251, s3, 59
	s_lshl_b32 s2, s0, 4
	s_add_u32 s4, s12, 0x1540000
	s_addc_u32 s5, s13, 0
	v_writelane_b32 v251, s4, 60
	v_mov_b32_e32 v192, 0x358637bd
	v_mov_b32_e32 v193, 0xf149f2ca
	v_writelane_b32 v251, s5, 61
	s_add_u32 s4, s12, 0x1500080
	s_addc_u32 s5, s13, 0
	v_writelane_b32 v251, s4, 62
	v_mbcnt_hi_u32_b32 v194, -1, v70
	v_mov_b32_e32 v195, 0x41b17218
	v_writelane_b32 v251, s5, 63
	s_add_u32 s4, s12, 0x1540080
	s_addc_u32 s5, s13, 0
	v_writelane_b32 v252, s4, 0
	v_mov_b64_e32 v[166:167], 0x80
	v_mov_b64_e32 v[168:169], 0x7f
	v_writelane_b32 v252, s5, 1
	s_add_u32 s4, s12, 0xc4200
	s_addc_u32 s5, s13, 0
	s_add_u32 s96, s12, 0xc4400
	s_addc_u32 s97, s13, 0
	s_add_u32 s54, s12, 0xc4500
	s_addc_u32 s55, s13, 0
	s_add_u32 s56, s12, 0xc4600
	s_addc_u32 s57, s13, 0
	s_add_u32 s58, s12, 0xc4700
	s_addc_u32 s59, s13, 0
	s_add_u32 s60, s12, 0xc4800
	s_addc_u32 s61, s13, 0
	s_add_u32 s64, s12, 0xc4900
	v_writelane_b32 v252, s4, 2
	s_addc_u32 s65, s13, 0
	v_mov_b32_e32 v240, v1
	v_writelane_b32 v252, s5, 3
	s_add_u32 s4, s12, 0xc4a00
	s_addc_u32 s5, s13, 0
	v_writelane_b32 v252, s4, 4
	v_mov_b32_e32 v241, v1
	v_mov_b32_e32 v242, v1
	v_writelane_b32 v252, s5, 5
	s_add_u32 s4, s12, 0xc4b00
	s_addc_u32 s5, s13, 0
	v_writelane_b32 v252, s4, 6
	v_mov_b32_e32 v243, v1
	v_bfrev_b32_e32 v196, 0.5
	v_writelane_b32 v252, s5, 7
	s_add_u32 s4, s12, 0xc4c00
	s_addc_u32 s5, s13, 0
	v_writelane_b32 v252, s4, 8
	v_mov_b32_e32 v197, 0x12000000
	v_mov_b64_e32 v[170:171], 0x200
	v_writelane_b32 v252, s5, 9
	s_add_u32 s4, s12, 0xc4d00
	s_addc_u32 s5, s13, 0
	v_writelane_b32 v252, s4, 10
	v_mov_b64_e32 v[172:173], 0x1ff
	v_mov_b32_e32 v198, 0x80
	v_writelane_b32 v252, s5, 11
	s_add_u32 s4, s12, 0xc4e00
	s_addc_u32 s5, s13, 0
	v_writelane_b32 v252, s4, 12
	v_mov_b64_e32 v[174:175], 0x800
	v_mov_b64_e32 v[176:177], 0x7ff
	v_writelane_b32 v252, s5, 13
	s_add_u32 s4, s12, 0xc4f00
	s_addc_u32 s5, s13, 0
	v_writelane_b32 v252, s4, 14
	s_mov_b64 s[84:85], 0x80
	s_waitcnt lgkmcnt(0)
	v_writelane_b32 v252, s5, 15
	s_add_u32 s4, s12, 0xc5000
	s_addc_u32 s5, s13, 0
	v_writelane_b32 v252, s4, 16
	s_barrier
	s_nop 0
	v_writelane_b32 v252, s5, 17
	s_add_u32 s4, s12, 0xc5100
	s_addc_u32 s5, s13, 0
	v_writelane_b32 v252, s4, 18
	s_nop 1
	v_writelane_b32 v252, s5, 19
	s_add_u32 s4, s12, 0xc5200
	s_addc_u32 s5, s13, 0
	v_writelane_b32 v252, s4, 20
	s_nop 1
	v_writelane_b32 v252, s5, 21
	s_add_u32 s4, s12, 0xc5300
	s_addc_u32 s5, s13, 0
	v_writelane_b32 v252, s4, 22
	s_nop 1
	v_writelane_b32 v252, s5, 23
	s_add_u32 s4, s12, 0xc7400
	s_addc_u32 s5, s13, 0
	v_writelane_b32 v252, s4, 24
	s_nop 1
	v_writelane_b32 v252, s5, 25
	s_add_u32 s4, s12, 0xc7500
	s_addc_u32 s5, s13, 0
	s_lshl_b32 s3, s51, 9
	s_add_u32 s30, s12, 0x33000000
	s_addc_u32 s31, s13, 0
	s_add_u32 s48, s12, 0x35000000
	v_writelane_b32 v252, s4, 26
	s_addc_u32 s49, s13, 0
	s_lshl_b32 s50, s14, 9
	v_writelane_b32 v252, s5, 27
	s_cmpk_lt_i32 s51, 0x200
	v_writelane_b32 v252, s3, 28
	s_cselect_b64 s[4:5], -1, 0
	s_lshl_b32 s3, s0, 6
	v_writelane_b32 v252, s4, 29
	s_cmpk_lt_i32 s51, 0x800
	s_nop 0
	v_writelane_b32 v252, s5, 30
	s_cselect_b64 s[4:5], -1, 0
	v_writelane_b32 v252, s4, 31
	s_nop 1
	v_writelane_b32 v252, s5, 32
	s_lshl_b32 s4, s0, 8
	s_add_u32 s5, s12, 0x5000
	v_writelane_b32 v252, s5, 33
	s_addc_u32 s5, s13, 0
	v_writelane_b32 v252, s5, 34
	s_cmp_lt_i32 s0, 0
	s_mul_i32 s5, s0, 17
	s_cselect_b32 s2, s5, s2
	s_mul_i32 s5, s0, 0x41
	s_cselect_b32 s3, s5, s3
	s_movk_i32 s5, 0x261
	s_cselect_b32 s5, s5, 0x260
	s_mul_i32 s5, s0, s5
	s_mulk_i32 s0, 0x101
	s_cselect_b32 s8, s0, s4
	s_add_i32 s5, s5, s1
	s_mul_hi_i32 s0, s5, 0x6bca1af3
	s_lshr_b32 s4, s0, 31
	s_ashr_i32 s0, s0, 7
	s_add_i32 s0, s0, s4
	s_mul_i32 s4, s0, 0x130
	s_sub_i32 s4, s5, s4
	s_bfe_u32 s5, s4, 0x3001c
	s_add_i32 s5, s4, s5
	s_and_b32 s6, s5, 0xfff8
	s_add_i32 s3, s3, s1
	s_sub_i32 s4, s4, s6
	s_ashr_i32 s6, s3, 31
	s_lshr_b32 s6, s6, 27
	s_add_i32 s6, s3, s6
	s_and_b32 s7, s6, 0xffe0
	s_sub_i32 s3, s3, s7
	s_bfe_i32 s7, s3, 0x80000
	s_bfe_u32 s7, s7, 0x3000c
	s_add_i32 s7, s3, s7
	s_and_b32 s9, s7, 0xf8
	s_lshl_b32 s0, s0, 3
	s_sext_i32_i16 s4, s4
	s_sub_i32 s3, s3, s9
	s_add_i32 s12, s0, s4
	s_add_i32 s10, s2, s1
;     __host__ __device__ bool next(int i, Unit& u) const {
;         const long L = (long)i * G + c; if (L >= nwg) return false;
;         int wgid = (int)L; { const int q = nwg / NXCD, r = nwg % NXCD, xcd = wgid % NXCD, off = wgid / NXCD; wgid = (xcd < r ? xcd * (q + 1) : r * (q + 1) + (xcd - r) * q) + off; }
;         const int nig = WGM * nN, gid = wgid / nig, fm = gid * WGM, gsz = (nM - fm) < WGM ? (nM - fm) : WGM;
;         u.pm = fm + ((wgid % nig) % gsz); u.pn = (wgid % nig) / gsz; return true;
; template <class Epi, class Sched, bool ALIGN_EPI = false, bool SP2 = false>
; __device__ __forceinline__ void gemm_phase(PG8_LAS unsigned char* lds, const Gemm g, const Sched& S, const Epi& E) {
;     ...
;     const char* cA = (const char*)g.A + (size_t)cur.pm * tstep; const char* cB = (const char*)g.Bt + (size_t)cur.pn * tstep;
	s_ashr_i32 s0, s6, 5
	s_bfe_i32 s2, s7, 0x80000
	s_lshl_b32 s0, s0, 3
	s_sext_i32_i16 s2, s2
	s_sext_i32_i8 s3, s3
	s_add_i32 s18, s0, s3
	s_ashr_i32 s0, s2, 3
	s_sext_i32_i16 s5, s5
	v_writelane_b32 v252, s0, 35
	s_lshr_b32 s0, s2, 3
	s_bfe_i64 s[6:7], s[0:1], 0x100000
	s_ashr_i32 s0, s5, 3
	v_writelane_b32 v252, s0, 36
	s_mov_b32 s2, s10
	s_ashr_i32 s11, s10, 31
	v_writelane_b32 v252, s2, 37
	s_ashr_i32 s19, s18, 31
	s_lshr_b32 s0, s5, 3
	v_writelane_b32 v252, s3, 38
	s_lshl_b64 s[2:3], s[10:11], 19
	v_writelane_b32 v252, s2, 39
	s_lshl_b64 s[4:5], s[6:7], 18
	v_readlane_b32 s10, v251, 34
	v_writelane_b32 v252, s3, 40
	s_lshl_b64 s[2:3], s[18:19], 18
	v_readlane_b32 s11, v251, 35
	s_add_u32 s4, s10, s4
	s_addc_u32 s5, s11, s5
	s_add_u32 s10, s4, 0x20000
	s_addc_u32 s11, s5, 0
	v_writelane_b32 v252, s10, 41
	s_add_u32 s2, s92, s2
	s_addc_u32 s3, s93, s3
	v_writelane_b32 v252, s11, 42
	s_add_u32 s10, s2, 0x20000
	v_writelane_b32 v252, s2, 43
	s_addc_u32 s11, s3, 0
	s_nop 0
	v_writelane_b32 v252, s3, 44
	v_writelane_b32 v252, s10, 45
	s_add_u32 s2, s4, 0x20080
	s_nop 0
	v_writelane_b32 v252, s11, 46
	v_writelane_b32 v252, s4, 47
	s_addc_u32 s3, s5, 0
	v_readlane_b32 s10, v251, 36
	v_writelane_b32 v252, s5, 48
	v_writelane_b32 v252, s2, 49
	s_lshl_b64 s[4:5], s[6:7], 19
	v_readlane_b32 s11, v251, 37
	v_writelane_b32 v252, s3, 50
	s_lshl_b64 s[2:3], s[18:19], 19
	s_add_u32 s10, s10, s4
	s_addc_u32 s11, s11, s5
	s_add_u32 s20, s10, 0x40000
	s_addc_u32 s21, s11, 0
	v_writelane_b32 v252, s20, 51
	s_nop 1
	v_writelane_b32 v252, s21, 52
	v_writelane_b32 v252, s16, 53
	s_add_u32 s16, s16, s2
	v_writelane_b32 v252, s17, 54
	s_addc_u32 s17, s17, s3
	s_add_u32 s20, s16, 0x40000
	v_writelane_b32 v252, s16, 55
	s_addc_u32 s21, s17, 0
	s_nop 0
	v_writelane_b32 v252, s17, 56
	v_writelane_b32 v252, s20, 57
	s_add_u32 s16, s10, 0x40080
	s_nop 0
	v_writelane_b32 v252, s21, 58
	v_writelane_b32 v252, s10, 59
	s_addc_u32 s17, s11, 0
	s_add_i32 s1, s8, s1
	s_ashr_i32 s8, s1, 31
	s_lshr_b32 s8, s8, 25
	s_add_i32 s8, s1, s8
	s_and_b32 s9, s8, 0xff80
	s_sub_i32 s1, s1, s9
	s_bfe_i32 s9, s1, 0x80000
	s_bfe_u32 s9, s9, 0x3000c
	s_add_i32 s9, s1, s9
	v_writelane_b32 v252, s11, 60
	s_and_b32 s10, s9, 0xf8
	s_sub_i32 s1, s1, s10
	s_ashr_i32 s8, s8, 7
	v_writelane_b32 v252, s16, 61
	s_lshl_b32 s8, s8, 3
	s_sext_i32_i8 s1, s1
	v_writelane_b32 v252, s17, 62
	s_add_i32 s16, s8, s1
	s_bfe_i32 s9, s9, 0x80000
	s_mov_b32 s10, s16
	s_sext_i32_i16 s9, s9
	s_ashr_i32 s17, s16, 31
	v_writelane_b32 v253, s10, 0
	s_lshr_b32 s8, s9, 3
	s_ashr_i32 s1, s9, 3
	v_writelane_b32 v253, s11, 1
	s_lshl_b64 s[10:11], s[16:17], 19
	s_bfe_i64 s[8:9], s[8:9], 0x100000
	v_writelane_b32 v253, s10, 2
	s_lshl_b64 s[8:9], s[8:9], 19
	v_writelane_b32 v252, s1, 63
	v_writelane_b32 v253, s11, 3
	v_readlane_b32 s10, v251, 40
	v_readlane_b32 s11, v251, 41
	s_add_u32 s8, s10, s8
	s_addc_u32 s9, s11, s9
	s_add_u32 s10, s8, 0x40000
	s_addc_u32 s11, s9, 0
	v_writelane_b32 v253, s10, 4
	s_nop 1
	v_writelane_b32 v253, s11, 5
	s_add_u32 s10, s8, 0x40080
	v_writelane_b32 v253, s8, 6
	s_addc_u32 s11, s9, 0
	s_lshl_b64 s[6:7], s[6:7], 21
	v_writelane_b32 v253, s9, 7
	v_writelane_b32 v253, s10, 8
	s_mov_b32 s8, s18
	s_nop 0
	v_writelane_b32 v253, s11, 9
	v_writelane_b32 v253, s8, 10
	v_readlane_b32 s10, v251, 42
	v_readlane_b32 s11, v251, 43
	v_writelane_b32 v253, s9, 11
	s_lshl_b64 s[8:9], s[18:19], 21
	s_add_u32 s6, s10, s6
	s_addc_u32 s7, s11, s7
	s_add_u32 s10, s6, 0x100000
	s_addc_u32 s11, s7, 0
	v_writelane_b32 v253, s10, 12
	s_add_u32 s8, s86, s8
	s_addc_u32 s9, s87, s9
	v_writelane_b32 v253, s11, 13
	s_add_u32 s10, s8, 0x100000
	v_writelane_b32 v253, s8, 14
	s_addc_u32 s11, s9, 0
	s_nop 0
	v_writelane_b32 v253, s9, 15
	v_writelane_b32 v253, s10, 16
	s_add_u32 s8, s6, 0x100080
	s_nop 0
	v_writelane_b32 v253, s11, 17
	v_writelane_b32 v253, s6, 18
	s_addc_u32 s9, s7, 0
	s_ashr_i32 s13, s12, 31
	v_writelane_b32 v253, s7, 19
	v_writelane_b32 v253, s8, 20
	s_mov_b32 s6, s12
	s_bfe_i64 s[0:1], s[0:1], 0x100000
	v_writelane_b32 v253, s9, 21
	v_writelane_b32 v253, s6, 22
	s_lshl_b64 s[0:1], s[0:1], 19
	s_mov_b64 s[10:11], s[62:63]
	v_writelane_b32 v253, s7, 23
	s_lshl_b64 s[6:7], s[12:13], 19
	v_writelane_b32 v253, s6, 24
	s_nop 1
	v_writelane_b32 v253, s7, 25
	v_readlane_b32 s6, v251, 32
	v_readlane_b32 s7, v251, 33
	s_add_u32 s0, s6, s0
	s_addc_u32 s1, s7, s1
	s_add_u32 s6, s0, 0x40000
	s_addc_u32 s7, s1, 0
	v_writelane_b32 v253, s6, 26
	s_nop 1
; __device__ __forceinline__ unsigned xb_xcc_id() { return (unsigned)__builtin_amdgcn_s_getreg((3 << 11) | 20) & 0xFu; }
; __global__ void __launch_bounds__(512, 2) fwd_mega(Args a) {
;     ...
;     if (threadIdx.x == 0) { bst[0] = 0u; bst[1] = 0u; }
;     __syncthreads();
;     (void)xcd_barrier_post(ctl + 4096, bst);
	v_writelane_b32 v253, s7, 27
	s_add_u32 s6, s0, 0x40080
	v_writelane_b32 v253, s0, 28
	s_addc_u32 s7, s1, 0
	s_nop 0
	v_writelane_b32 v253, s1, 29
	v_readlane_b32 s0, v251, 38
	v_readlane_b32 s1, v251, 39
	s_add_u32 s4, s0, s4
	s_addc_u32 s5, s1, s5
	v_writelane_b32 v253, s6, 30
	s_add_u32 s0, s4, 0x40000
	s_addc_u32 s1, s5, 0
	v_writelane_b32 v253, s7, 31
	v_writelane_b32 v253, s0, 32
	s_add_u32 s2, s88, s2
	s_addc_u32 s3, s89, s3
	v_writelane_b32 v253, s1, 33
	s_mul_i32 s0, s15, s14
	s_mul_i32 s0, s0, s33
	v_writelane_b32 v253, s0, 34
	s_add_u32 s0, s2, 0x40000
	v_writelane_b32 v253, s2, 35
	s_addc_u32 s1, s3, 0
	s_nop 0
	v_writelane_b32 v253, s3, 36
	v_writelane_b32 v253, s0, 37
	s_mov_b32 s2, 0
	s_nop 0
	v_writelane_b32 v253, s1, 38
	s_add_u32 s0, s4, 0x40080
	v_writelane_b32 v253, s4, 39
	s_addc_u32 s1, s5, 0
	s_bitcmp1_b32 s51, 0
	v_writelane_b32 v253, s5, 40
	v_writelane_b32 v253, s0, 41
	s_nop 1
	v_writelane_b32 v253, s1, 42
	s_cselect_b64 s[0:1], -1, 0
	v_writelane_b32 v253, s0, 43
	s_bitcmp1_b32 s14, 0
	s_nop 0
	v_writelane_b32 v253, s1, 44
	s_mov_b32 s0, s14
	v_writelane_b32 v253, s0, 45
	s_cselect_b64 s[0:1], -1, 0
	v_writelane_b32 v253, s0, 46
	s_nop 1
	v_writelane_b32 v253, s1, 47
	s_lshl_b32 s0, s51, 12
	v_writelane_b32 v253, s0, 48
	s_lshl_b32 s0, s14, 12
	v_writelane_b32 v253, s0, 49
	s_add_i32 s0, 0, 0x23ff0
	v_writelane_b32 v253, s0, 50
	s_add_i32 s0, 0, 0x23ff4
	v_writelane_b32 v253, s0, 51
	s_add_i32 s0, 0, 0xc800
	v_writelane_b32 v253, s0, 52
	s_add_i32 s0, 0, 0x13300
	v_writelane_b32 v253, s0, 53
	s_add_i32 s0, 0, 0x12b00
	v_writelane_b32 v253, s0, 54
	s_add_i32 s0, 0, 0x11d00
	v_writelane_b32 v253, s0, 55
	s_add_i32 s0, 0, 0x12600
	v_writelane_b32 v253, s0, 56
	s_add_i32 s0, 0, 0x11e00
	v_writelane_b32 v253, s0, 57
	s_add_i32 s0, 0, 0x11c00
	v_writelane_b32 v253, s0, 58
	s_add_i32 s0, 0, 0x11c20
	v_writelane_b32 v253, s0, 59
	s_add_i32 s0, 0, 0x11c40
	v_writelane_b32 v253, s0, 60
	s_add_i32 s0, 0, 0x11c60
	v_writelane_b32 v253, s0, 61
	s_add_i32 s0, 0, 0x11c80
	v_writelane_b32 v253, s0, 62
	s_add_i32 s0, 0, 0x11ca0
	v_writelane_b32 v253, s0, 63
	s_add_i32 s0, 0, 0x11cc0
	v_writelane_b32 v254, s0, 0
	s_add_i32 s0, 0, 0x11ce0
	v_writelane_b32 v254, s0, 1
	s_add_i32 s0, 0, 0x13600
	v_writelane_b32 v254, s0, 2
	s_add_i32 s0, 0, 0x9694
	v_writelane_b32 v254, s0, 3
	s_mov_b64 s[0:1], -1
	v_writelane_b32 v254, s0, 4
	s_mov_b64 s[14:15], s[66:67]
	s_nop 0
	v_writelane_b32 v254, s1, 5
	s_mov_b32 s1, 0
	v_writelane_b32 v254, s0, 6
	s_nop 1
	v_writelane_b32 v254, s1, 7
	s_mov_b64 s[0:1], s[52:53]
	v_writelane_b32 v254, s0, 8
	s_nop 1
	v_writelane_b32 v254, s1, 9
	v_writelane_b32 v254, s2, 10
	v_writelane_b32 v254, s3, 11
	v_writelane_b32 v254, s4, 12
	v_writelane_b32 v254, s5, 13
	v_writelane_b32 v254, s6, 14
	v_writelane_b32 v254, s7, 15
	v_writelane_b32 v254, s8, 16
	v_writelane_b32 v254, s9, 17
	v_writelane_b32 v254, s10, 18
	v_writelane_b32 v254, s11, 19
	v_writelane_b32 v254, s12, 20
	v_writelane_b32 v254, s13, 21
	v_writelane_b32 v254, s14, 22
	v_writelane_b32 v254, s15, 23
	v_writelane_b32 v254, s54, 24
	s_nop 1
	v_writelane_b32 v254, s55, 25
	v_writelane_b32 v254, s56, 26
	s_nop 1
	v_writelane_b32 v254, s57, 27
	v_writelane_b32 v254, s58, 28
	s_nop 1
	v_writelane_b32 v254, s59, 29
	v_writelane_b32 v254, s60, 30
	s_nop 1
	v_writelane_b32 v254, s61, 31
	v_writelane_b32 v254, s64, 32
	s_nop 1
	v_writelane_b32 v254, s65, 33
	v_writelane_b32 v254, s30, 34
	s_nop 1
	v_writelane_b32 v254, s31, 35
	v_writelane_b32 v254, s48, 36
	s_nop 1
	v_writelane_b32 v254, s49, 37
	v_writelane_b32 v254, s50, 38
	v_writelane_b32 v254, s51, 39
	v_writelane_b32 v254, s86, 40
	s_nop 1
	v_writelane_b32 v254, s87, 41
	v_writelane_b32 v254, s88, 42
	s_nop 1
	v_writelane_b32 v254, s89, 43
	v_writelane_b32 v254, s90, 44
	s_nop 1
	v_writelane_b32 v254, s91, 45
	v_writelane_b32 v254, s92, 46
	s_nop 1
	v_writelane_b32 v254, s93, 47
	v_writelane_b32 v254, s94, 48
	v_writelane_b32 v254, s95, 49
	v_writelane_b32 v254, s96, 50
	s_nop 1
	v_writelane_b32 v254, s97, 51
	s_getreg_b32 s98, hwreg(HW_REG_XCC_ID, 0, 4)
	s_lshl_b32 s98, 1, s98
	v_mov_b32_e32 v0, s98
	s_and_b32 s99, s51, 7
	s_lshl_b32 s99, s99, 2
	v_readlane_b32 s100, v252, 26
	v_readlane_b32 s101, v252, 27
	s_add_u32 s100, s100, s99
	s_addc_u32 s101, s101, 0
	v_cmp_eq_u32_e32 vcc, 0, v188
	s_and_saveexec_b64 s[98:99], vcc
	s_nop 3
	global_atomic_or v1, v0, s[100:101] offset:32
	s_or_b64 exec, exec, s[98:99]
	s_branch .LBB0_146

; __device__ __forceinline__ unsigned xb_ld(unsigned* p)              { return __hip_atomic_load(p, __ATOMIC_RELAXED, __HIP_MEMORY_SCOPE_AGENT); }
; __device__ __forceinline__ unsigned xb_add(unsigned* p, unsigned v) { return __hip_atomic_fetch_add(p, v, __ATOMIC_RELAXED, __HIP_MEMORY_SCOPE_AGENT); }
; #define XB_SPIN(cond, bar) do { unsigned _sp = 0; while (cond) { __builtin_amdgcn_s_sleep(1); \
;     if ((++_sp & 255u) == 0u) { if (xb_ld(&(bar)[XB_TMO])) break; if (_sp > XB_SPIN_CAP) { atomicAdd(&(bar)[XB_TMO], 1u); break; } } } } while (0)
; __device__ __forceinline__ void xcd_barrier(const XcdBarrier& b) {
;     ...
;         const unsigned old = xb_add(&bar[XB_XSUB(b.x)], 1u);
;         const unsigned gen = old / nloc;
;         if (old + 1u == (gen + 1u) * nloc) {
;             __builtin_amdgcn_fence(__ATOMIC_RELEASE, "agent");
;             asm volatile("s_waitcnt vmcnt(0)" ::: "memory");
;             const unsigned og = xb_add(&bar[XB_TOP], 1u);
;             const unsigned tg = og / nx;
;             if (og + 1u == (tg + 1u) * nx) xb_add(&bar[XB_TOPGEN], 1u);
;             else XB_SPIN(xb_ld(&bar[XB_TOPGEN]) == tg, bar);
.LBB0_618:
	s_andn2_saveexec_b64 s[6:7], s[6:7]
	s_cbranch_execz .LBB0_638
	s_mov_b64 s[6:7], exec
	buffer_wbl2 sc1
	s_waitcnt lgkmcnt(0)
	s_waitcnt vmcnt(0)
	v_readlane_b32 s100, v252, 26
	v_readlane_b32 s101, v252, 27
	s_nop 4
	global_load_dwordx4 v[4:7], v1, s[100:101] offset:32 sc1
	global_load_dwordx4 v[8:11], v1, s[100:101] offset:48 sc1
	s_waitcnt vmcnt(0)
	v_add_u32_e32 v12, -1, v4
	v_and_b32_e32 v12, v12, v4
	v_min_u32_e32 v13, v4, v5
	v_add_u32_e32 v14, -1, v5
	v_and_or_b32 v12, v14, v5, v12
	v_min_u32_e32 v13, v13, v5
	v_add_u32_e32 v14, -1, v6
	v_and_or_b32 v12, v14, v6, v12
	v_min_u32_e32 v13, v13, v6
	v_add_u32_e32 v14, -1, v7
	v_and_or_b32 v12, v14, v7, v12
	v_min_u32_e32 v13, v13, v7
	v_add_u32_e32 v14, -1, v8
	v_and_or_b32 v12, v14, v8, v12
	v_min_u32_e32 v13, v13, v8
	v_add_u32_e32 v14, -1, v9
	v_and_or_b32 v12, v14, v9, v12
	v_min_u32_e32 v13, v13, v9
	v_add_u32_e32 v14, -1, v10
	v_and_or_b32 v12, v14, v10, v12
	v_min_u32_e32 v13, v13, v10
	v_add_u32_e32 v14, -1, v11
	v_and_or_b32 v12, v14, v11, v12
	v_min_u32_e32 v13, v13, v11
	v_cmp_eq_u32_e32 vcc, 0, v13
	s_nop 1
	v_cndmask_b32_e64 v13, 0, 1, vcc
	v_or_b32_e32 v12, v12, v13
	s_nop 0
	v_readfirstlane_b32 s98, v12
	s_cmp_eq_u32 s98, 0
	s_cbranch_scc1 .LBB0_635
	v_mbcnt_lo_u32_b32 v0, s6, 0
	v_mbcnt_hi_u32_b32 v0, s7, v0
	v_cmp_eq_u32_e32 vcc, 0, v0
	s_and_saveexec_b64 s[8:9], vcc
	s_cbranch_execz .LBB0_621
	s_bcnt1_i32_b64 s6, s[6:7]
	v_mov_b32_e32 v3, s6
	v_readlane_b32 s6, v252, 24
	v_readlane_b32 s7, v252, 25
	s_nop 4
	global_atomic_add v3, v1, v3, s[6:7] sc0

; __device__ __forceinline__ unsigned xb_ld(unsigned* p)              { return __hip_atomic_load(p, __ATOMIC_RELAXED, __HIP_MEMORY_SCOPE_AGENT); }
; __device__ __forceinline__ unsigned xb_add(unsigned* p, unsigned v) { return __hip_atomic_fetch_add(p, v, __ATOMIC_RELAXED, __HIP_MEMORY_SCOPE_AGENT); }
; #define XB_SPIN(cond, bar) do { unsigned _sp = 0; while (cond) { __builtin_amdgcn_s_sleep(1); \
;     if ((++_sp & 255u) == 0u) { if (xb_ld(&(bar)[XB_TMO])) break; if (_sp > XB_SPIN_CAP) { atomicAdd(&(bar)[XB_TMO], 1u); break; } } } } while (0)
; __device__ __forceinline__ void xcd_barrier(const XcdBarrier& b) {
;     ...
;         const unsigned old = xb_add(&bar[XB_XSUB(b.x)], 1u);
;         const unsigned gen = old / nloc;
;         if (old + 1u == (gen + 1u) * nloc) {
;             __builtin_amdgcn_fence(__ATOMIC_RELEASE, "agent");
;             asm volatile("s_waitcnt vmcnt(0)" ::: "memory");
;             const unsigned og = xb_add(&bar[XB_TOP], 1u);
;             const unsigned tg = og / nx;
;             if (og + 1u == (tg + 1u) * nx) xb_add(&bar[XB_TOPGEN], 1u);
;             else XB_SPIN(xb_ld(&bar[XB_TOPGEN]) == tg, bar);
.LBB0_706:
	s_andn2_saveexec_b64 s[6:7], s[6:7]
	s_cbranch_execz .LBB0_726
	s_mov_b64 s[6:7], exec
	buffer_wbl2 sc1
	s_waitcnt lgkmcnt(0)
	s_waitcnt vmcnt(0)
	v_readlane_b32 s100, v252, 26
	v_readlane_b32 s101, v252, 27
	s_nop 4
	global_load_dwordx4 v[4:7], v1, s[100:101] offset:32 sc1
	global_load_dwordx4 v[8:11], v1, s[100:101] offset:48 sc1
	s_waitcnt vmcnt(0)
	v_add_u32_e32 v12, -1, v4
	v_and_b32_e32 v12, v12, v4
	v_min_u32_e32 v13, v4, v5
	v_add_u32_e32 v14, -1, v5
	v_and_or_b32 v12, v14, v5, v12
	v_min_u32_e32 v13, v13, v5
	v_add_u32_e32 v14, -1, v6
	v_and_or_b32 v12, v14, v6, v12
	v_min_u32_e32 v13, v13, v6
	v_add_u32_e32 v14, -1, v7
	v_and_or_b32 v12, v14, v7, v12
	v_min_u32_e32 v13, v13, v7
	v_add_u32_e32 v14, -1, v8
	v_and_or_b32 v12, v14, v8, v12
	v_min_u32_e32 v13, v13, v8
	v_add_u32_e32 v14, -1, v9
	v_and_or_b32 v12, v14, v9, v12
	v_min_u32_e32 v13, v13, v9
	v_add_u32_e32 v14, -1, v10
	v_and_or_b32 v12, v14, v10, v12
	v_min_u32_e32 v13, v13, v10
	v_add_u32_e32 v14, -1, v11
	v_and_or_b32 v12, v14, v11, v12
	v_min_u32_e32 v13, v13, v11
	v_cmp_eq_u32_e32 vcc, 0, v13
	s_nop 1
	v_cndmask_b32_e64 v13, 0, 1, vcc
	v_or_b32_e32 v12, v12, v13
	s_nop 0
	v_readfirstlane_b32 s98, v12
	s_cmp_eq_u32 s98, 0
	s_cbranch_scc1 .LBB0_723
	v_mbcnt_lo_u32_b32 v0, s6, 0
	v_mbcnt_hi_u32_b32 v0, s7, v0
	v_cmp_eq_u32_e32 vcc, 0, v0
	s_and_saveexec_b64 s[14:15], vcc
	s_cbranch_execz .LBB0_709
	s_bcnt1_i32_b64 s6, s[6:7]
	v_mov_b32_e32 v3, s6
	v_readlane_b32 s6, v252, 24
	v_readlane_b32 s7, v252, 25
	s_nop 4
	global_atomic_add v3, v1, v3, s[6:7] sc0

; __device__ __forceinline__ unsigned xb_ld(unsigned* p)              { return __hip_atomic_load(p, __ATOMIC_RELAXED, __HIP_MEMORY_SCOPE_AGENT); }
; __device__ __forceinline__ unsigned xb_add(unsigned* p, unsigned v) { return __hip_atomic_fetch_add(p, v, __ATOMIC_RELAXED, __HIP_MEMORY_SCOPE_AGENT); }
; #define XB_SPIN(cond, bar) do { unsigned _sp = 0; while (cond) { __builtin_amdgcn_s_sleep(1); \
;     if ((++_sp & 255u) == 0u) { if (xb_ld(&(bar)[XB_TMO])) break; if (_sp > XB_SPIN_CAP) { atomicAdd(&(bar)[XB_TMO], 1u); break; } } } } while (0)
; __device__ __forceinline__ void xcd_barrier(const XcdBarrier& b) {
;     ...
;         const unsigned old = xb_add(&bar[XB_XSUB(b.x)], 1u);
;         const unsigned gen = old / nloc;
;         if (old + 1u == (gen + 1u) * nloc) {
;             __builtin_amdgcn_fence(__ATOMIC_RELEASE, "agent");
;             asm volatile("s_waitcnt vmcnt(0)" ::: "memory");
;             const unsigned og = xb_add(&bar[XB_TOP], 1u);
;             const unsigned tg = og / nx;
;             if (og + 1u == (tg + 1u) * nx) xb_add(&bar[XB_TOPGEN], 1u);
;             else XB_SPIN(xb_ld(&bar[XB_TOPGEN]) == tg, bar);
.LBB0_778:
	s_andn2_saveexec_b64 s[6:7], s[6:7]
	s_cbranch_execz .LBB0_798
	s_mov_b64 s[10:11], exec
	buffer_wbl2 sc1
	s_waitcnt lgkmcnt(0)
	s_waitcnt vmcnt(0)
	v_readlane_b32 s100, v252, 26
	v_readlane_b32 s101, v252, 27
	s_nop 4
	global_load_dwordx4 v[4:7], v1, s[100:101] offset:32 sc1
	global_load_dwordx4 v[8:11], v1, s[100:101] offset:48 sc1
	s_waitcnt vmcnt(0)
	v_add_u32_e32 v12, -1, v4
	v_and_b32_e32 v12, v12, v4
	v_min_u32_e32 v13, v4, v5
	v_add_u32_e32 v14, -1, v5
	v_and_or_b32 v12, v14, v5, v12
	v_min_u32_e32 v13, v13, v5
	v_add_u32_e32 v14, -1, v6
	v_and_or_b32 v12, v14, v6, v12
	v_min_u32_e32 v13, v13, v6
	v_add_u32_e32 v14, -1, v7
	v_and_or_b32 v12, v14, v7, v12
	v_min_u32_e32 v13, v13, v7
	v_add_u32_e32 v14, -1, v8
	v_and_or_b32 v12, v14, v8, v12
	v_min_u32_e32 v13, v13, v8
	v_add_u32_e32 v14, -1, v9
	v_and_or_b32 v12, v14, v9, v12
	v_min_u32_e32 v13, v13, v9
	v_add_u32_e32 v14, -1, v10
	v_and_or_b32 v12, v14, v10, v12
	v_min_u32_e32 v13, v13, v10
	v_add_u32_e32 v14, -1, v11
	v_and_or_b32 v12, v14, v11, v12
	v_min_u32_e32 v13, v13, v11
	v_cmp_eq_u32_e32 vcc, 0, v13
	s_nop 1
	v_cndmask_b32_e64 v13, 0, 1, vcc
	v_or_b32_e32 v12, v12, v13
	s_nop 0
	v_readfirstlane_b32 s98, v12
	s_cmp_eq_u32 s98, 0
	s_cbranch_scc1 .LBB0_795
	v_mbcnt_lo_u32_b32 v0, s10, 0
	v_mbcnt_hi_u32_b32 v0, s11, v0
	v_cmp_eq_u32_e32 vcc, 0, v0
	s_and_saveexec_b64 s[12:13], vcc
	s_cbranch_execz .LBB0_781
	s_bcnt1_i32_b64 s10, s[10:11]
	v_mov_b32_e32 v3, s10
	v_readlane_b32 s10, v252, 24
	v_readlane_b32 s11, v252, 25
	s_nop 4
	global_atomic_add v3, v1, v3, s[10:11] sc0
